# prologue: once-read f32 input streams (w_mod, weight matrices, expert tables) loaded with nt
# speedup vs baseline: 1.0093x; 1.0016x over previous
; __device__ __forceinline__ void prologue_phase(const Ctx& F, CParams& P) {
;     ...
;         for (int it = F.vcu; it < DEPTH * 192; it += F.G) {
;             const int l = it / 192, n0 = (it % 192) * 64;
;             const float* wp = P.w_mod + ((size_t)l * DM + F.wid * 256) * 12288 + n0 + F.lane;
;             float a0 = 0.f, a1 = 0.f, a2 = 0.f;
; #pragma unroll 8
;             for (int k = 0; k < 256; ++k) { const float w = wp[(size_t)k * 12288]; const int kk = F.wid * 256 + k; a0 += sv[kk] * w; a1 += sv[DM + kk] * w; a2 += sv[2 * DM + kk] * w; }
;             part[(F.wid * 3 + 0) * 64 + F.lane] = a0; part[(F.wid * 3 + 1) * 64 + F.lane] = a1; part[(F.wid * 3 + 2) * 64 + F.lane] = a2;
;             __syncthreads();
;             if (F.wid < 3) { float s = 0.f;
; #pragma unroll
;                 for (int w = 0; w < 8; ++w) s += part[(w * 3 + F.wid) * 64 + F.lane];
;                 mod[((size_t)l * 3 + F.wid) * 12288 + n0 + F.lane] = s + P.b_mod[(size_t)l * 12288 + n0 + F.lane]; }
;             __syncthreads();
;         }
.LBB0_21:
	v_lshl_add_u64 v[10:11], v[0:1], 0, s[16:17]
	v_add_co_u32_e32 v12, vcc, s23, v10
	global_load_dword v34, v[10:11], off nt
	s_nop 0
	v_addc_co_u32_e32 v13, vcc, 0, v11, vcc
	v_add_co_u32_e32 v14, vcc, s24, v10
	v_mov_b32_e32 v9, s15
	s_nop 0
	v_addc_co_u32_e32 v15, vcc, 0, v11, vcc
	v_add_co_u32_e32 v16, vcc, s25, v10
	s_add_i32 s15, s15, 32
	s_nop 0
	v_addc_co_u32_e32 v17, vcc, 0, v11, vcc
	v_add_co_u32_e32 v18, vcc, s26, v10
	s_add_u32 s16, s16, 0x60000
	s_nop 0
	v_addc_co_u32_e32 v19, vcc, 0, v11, vcc
	v_add_co_u32_e32 v20, vcc, s27, v10
	s_addc_u32 s17, s17, 0
	s_nop 0
	v_addc_co_u32_e32 v21, vcc, 0, v11, vcc
	v_add_co_u32_e32 v22, vcc, s31, v10
	s_cmp_eq_u32 s16, 0xc00000
	s_nop 0
	v_addc_co_u32_e32 v23, vcc, 0, v11, vcc
	v_add_co_u32_e32 v10, vcc, s35, v10
	s_nop 1
	v_addc_co_u32_e32 v11, vcc, 0, v11, vcc
	global_load_dword v36, v[12:13], off nt
	global_load_dword v38, v[14:15], off nt
	global_load_dword v40, v[16:17], off nt
	global_load_dword v42, v[18:19], off nt
	global_load_dword v44, v[20:21], off nt
	global_load_dword v46, v[22:23], off nt
	global_load_dword v48, v[10:11], off nt
	ds_read_b128 v[10:13], v9
	ds_read_b128 v[14:17], v9 offset:16
	ds_read_b128 v[18:21], v9 offset:8192
	ds_read_b128 v[22:25], v9 offset:8208
	ds_read_b128 v[26:29], v9 offset:16384
	ds_read_b128 v[30:33], v9 offset:16400
	s_waitcnt lgkmcnt(5)
	v_mov_b32_e32 v50, v10
	s_waitcnt lgkmcnt(3)
	v_mov_b32_e32 v51, v18
	v_mov_b32_e32 v18, v11
	v_mov_b32_e32 v10, v12
	v_mov_b32_e32 v11, v20
	v_mov_b32_e32 v20, v13
	v_mov_b32_e32 v12, v14
	s_waitcnt lgkmcnt(2)
	v_mov_b32_e32 v13, v22
	v_mov_b32_e32 v22, v15
	v_mov_b32_e32 v14, v16
	v_mov_b32_e32 v15, v24
	v_mov_b32_e32 v24, v17
	s_waitcnt vmcnt(7)
	v_pk_fma_f32 v[2:3], v[34:35], v[50:51], v[2:3] op_sel_hi:[0,1,1]
	s_waitcnt lgkmcnt(1)
	v_fmac_f32_e32 v7, v34, v26
	s_waitcnt vmcnt(6)
	v_pk_fma_f32 v[2:3], v[36:37], v[18:19], v[2:3] op_sel_hi:[0,1,1]
	v_fmac_f32_e32 v7, v36, v27
	s_waitcnt vmcnt(5)
	v_pk_fma_f32 v[2:3], v[38:39], v[10:11], v[2:3] op_sel_hi:[0,1,1]
	v_fmac_f32_e32 v7, v38, v28
	s_waitcnt vmcnt(4)
	v_pk_fma_f32 v[2:3], v[40:41], v[20:21], v[2:3] op_sel_hi:[0,1,1]
	v_fmac_f32_e32 v7, v40, v29
	s_waitcnt vmcnt(3)
	v_pk_fma_f32 v[2:3], v[42:43], v[12:13], v[2:3] op_sel_hi:[0,1,1]
	s_waitcnt lgkmcnt(0)
	v_fmac_f32_e32 v7, v42, v30
	s_waitcnt vmcnt(2)
	v_pk_fma_f32 v[2:3], v[44:45], v[22:23], v[2:3] op_sel_hi:[0,1,1]
	v_fmac_f32_e32 v7, v44, v31
	s_waitcnt vmcnt(1)
	v_pk_fma_f32 v[2:3], v[46:47], v[14:15], v[2:3] op_sel_hi:[0,1,1]
	v_fmac_f32_e32 v7, v46, v32
	s_waitcnt vmcnt(0)
	v_pk_fma_f32 v[2:3], v[48:49], v[24:25], v[2:3] op_sel_hi:[0,1,1]
	v_fmac_f32_e32 v7, v48, v33
	s_cbranch_scc0 .LBB0_21
	s_and_b64 vcc, exec, s[2:3]
	ds_write_b32 v4, v2 offset:24576
	ds_write2st64_b32 v5, v3, v7 offset0:97 offset1:98
	s_waitcnt lgkmcnt(0)
	s_barrier
	s_cbranch_vccnz .LBB0_19
	s_mul_i32 s16, s14, 0xc000
	s_mul_hi_i32 s15, s14, 0xc000
	s_add_u32 s16, s6, s16
	s_addc_u32 s15, s7, s15
	s_add_u32 s16, s16, s12
	s_addc_u32 s17, s15, s13
	v_lshlrev_b64 v[0:1], 2, v[64:65]
	v_lshl_add_u64 v[2:3], s[16:17], 0, v[0:1]
	global_load_dword v7, v[2:3], off nt
	ds_read2st64_b32 v[2:3], v6 offset0:96 offset1:99
	ds_read2st64_b32 v[10:11], v6 offset0:102 offset1:105
	ds_read2st64_b32 v[12:13], v6 offset0:108 offset1:111
	ds_read2st64_b32 v[14:15], v6 offset0:114 offset1:117
	s_mul_hi_i32 s15, s14, 3
	s_mul_i32 s14, s14, 3
	s_waitcnt lgkmcnt(3)
	v_add_f32_e32 v2, 0, v2
	s_add_u32 s14, s14, s30
	v_add_f32_e32 v2, v2, v3
	s_addc_u32 s15, s15, s21
	s_mul_hi_u32 s16, s14, 0xc000
	s_waitcnt lgkmcnt(2)
	v_add_f32_e32 v2, v2, v10
	s_mul_i32 s15, s15, 0xc000
	s_mul_i32 s14, s14, 0xc000
	v_add_f32_e32 v2, v2, v11
	s_add_i32 s16, s16, s15
	s_waitcnt lgkmcnt(1)
	v_add_f32_e32 v2, v2, v12
	s_add_u32 s14, s9, s14
	v_add_f32_e32 v2, v2, v13
	s_addc_u32 s15, s18, s16
	s_waitcnt lgkmcnt(0)
	v_add_f32_e32 v2, v2, v14
	s_add_u32 s12, s14, s12
	v_add_f32_e32 v2, v2, v15
	s_addc_u32 s13, s15, s13
	v_lshl_add_u64 v[0:1], s[12:13], 0, v[0:1]
	s_waitcnt vmcnt(0)
	v_add_f32_e32 v2, v2, v7
	global_store_dword v[0:1], v2, off
	s_branch .LBB0_19

;     ...
;     for (int it = F.vcu; it < total; it += F.G) {
;         const int mat = it / per, rem = it % per, tn = rem / ntk, tk = rem % ntk, k0 = tk * 64, n0 = tn * 64;
;         const float* s = src + (size_t)mat * K * N; bf16_t* d = dst + (size_t)mat * Npad * K;
;         __syncthreads();
;         { const int r = F.tid >> 4, c4 = (F.tid & 15) * 4;
; #pragma unroll
;           for (int i = 0; i < 2; ++i) { const int rr = r + i * 32; f32x4 v = (f32x4){0.f, 0.f, 0.f, 0.f};
;               const int sn0 = n0 < pad_at ? n0 : n0 - pad_len;
;               if (sn0 + c4 < N && !(n0 >= pad_at && n0 < pad_at + pad_len)) v = *(const f32x4*)(s + (size_t)(k0 + rr) * N + sn0 + c4);
;               tile[rr * 65 + c4 + 0] = v[0]; tile[rr * 65 + c4 + 1] = v[1]; tile[rr * 65 + c4 + 2] = v[2]; tile[rr * 65 + c4 + 3] = v[3]; } }
.LBB0_59:
	s_mul_hi_i32 s4, s17, 0x38e38e39
	s_lshr_b32 s5, s4, 31
	s_ashr_i32 s19, s4, 9
	s_add_i32 s19, s19, s5
	s_mul_i32 s4, s19, 0xfffff700
	s_add_i32 s5, s17, s4
	s_bfe_u32 s4, s5, 0x5001a
	s_add_i32 s4, s5, s4
	s_sext_i32_i16 s6, s4
	s_and_b32 s4, s4, 0xffe0
	s_sub_i32 s4, s5, s4
	s_sext_i32_i16 s4, s4
	s_lshl_b32 s18, s6, 1
	s_lshl_b32 s4, s4, 6
	s_andn2_b32 s18, s18, 63
	s_cmpk_lt_i32 s5, 0x6a0
	s_cselect_b32 s6, 0, 0xffffff40
	s_add_i32 s12, s18, s6
	s_addk_i32 s5, 0xf960
	v_or_b32_e32 v0, s12, v4
	s_cmpk_gt_u32 s5, 0x5f
	v_cmp_gt_i32_e32 vcc, s15, v0
	s_cselect_b64 s[6:7], -1, 0
	s_and_b64 s[6:7], vcc, s[6:7]
	s_waitcnt lgkmcnt(0)
	s_barrier
	s_and_saveexec_b64 s[20:21], s[6:7]
	s_xor_b64 s[6:7], exec, s[20:21]
	s_cbranch_execz .LBB0_61
	s_mul_i32 s13, s19, 0x2280000
	s_mul_hi_i32 s5, s19, 0x2280000
	s_add_u32 s20, s2, s13
	s_addc_u32 s5, s3, s5
	s_ashr_i32 s13, s12, 31
	s_lshl_b64 s[12:13], s[12:13], 2
	s_add_u32 s12, s20, s12
	s_addc_u32 s13, s5, s13
	v_lshl_add_u64 v[0:1], s[12:13], 0, v[6:7]
	v_add_u32_e32 v18, s4, v9
	v_mad_i64_i32 v[2:3], s[12:13], v18, s16, v[0:1]
	global_load_dwordx4 v[22:25], v[2:3], off nt
	v_add_u32_e32 v2, 32, v18
	v_mad_i64_i32 v[0:1], s[12:13], v2, s16, v[0:1]
	global_load_dwordx4 v[0:3], v[0:1], off nt
	s_waitcnt vmcnt(1)
	ds_write2_b32 v5, v22, v23 offset1:1
	ds_write2_b32 v12, v24, v25 offset1:1

;     ...
;     for (int it = F.vcu; it < total; it += F.G) {
;         const int mat = it / per, rem = it % per, tn = rem / ntk, tk = rem % ntk, k0 = tk * 64, n0 = tn * 64;
;         const float* s = src + (size_t)mat * K * N; bf16_t* d = dst + (size_t)mat * Npad * K;
;         __syncthreads();
;         { const int r = F.tid >> 4, c4 = (F.tid & 15) * 4;
; #pragma unroll
;           for (int i = 0; i < 2; ++i) { const int rr = r + i * 32; f32x4 v = (f32x4){0.f, 0.f, 0.f, 0.f};
;               const int sn0 = n0 < pad_at ? n0 : n0 - pad_len;
;               if (sn0 + c4 < N && !(n0 >= pad_at && n0 < pad_at + pad_len)) v = *(const f32x4*)(s + (size_t)(k0 + rr) * N + sn0 + c4);
;               tile[rr * 65 + c4 + 0] = v[0]; tile[rr * 65 + c4 + 1] = v[1]; tile[rr * 65 + c4 + 2] = v[2]; tile[rr * 65 + c4 + 3] = v[3]; } }
;         __syncthreads();
;         { const int n = F.tid >> 3, kc = (F.tid & 7) * 8; float v[8];
; #pragma unroll
;           for (int e = 0; e < 8; ++e) { v[e] = tile[(kc + e) * 65 + n]; if (gain) v[e] *= gain[(size_t)mat * K + k0 + kc + e]; }
.LBB0_66:
	s_mul_hi_i32 s12, s19, 0x38e38e39
	s_lshr_b32 s13, s12, 31
	s_ashr_i32 s20, s12, 6
	s_add_i32 s20, s20, s13
	s_mul_i32 s12, s20, 0xfffffee0
	s_add_i32 s12, s19, s12
	s_mul_i32 s13, s12, 0x2aab
	s_lshr_b32 s14, s13, 31
	s_ashr_i32 s13, s13, 17
	s_add_i32 s13, s13, s14
	s_mul_i32 s14, s13, 12
	s_sub_i32 s12, s12, s14
	s_sext_i32_i16 s12, s12
	s_lshl_b32 s12, s12, 6
	s_lshl_b32 s14, s13, 6
	s_mul_i32 s15, s20, 0x480000
	s_mul_hi_i32 s13, s20, 0x480000
	s_add_u32 s21, s6, s15
	s_addc_u32 s13, s7, s13
	s_ashr_i32 s15, s14, 31
	s_lshl_b64 s[22:23], s[14:15], 2
	s_add_u32 s22, s21, s22
	s_addc_u32 s23, s13, s23
	v_lshl_add_u64 v[4:5], s[22:23], 0, v[14:15]
	v_add_u32_e32 v6, s12, v9
	v_mad_i64_i32 v[0:1], s[22:23], v6, s17, v[4:5]
	s_barrier
	global_load_dwordx4 v[0:3], v[0:1], off nt
	v_add_u32_e32 v6, 32, v6
	v_mad_i64_i32 v[4:5], s[22:23], v6, s17, v[4:5]
	global_load_dwordx4 v[4:7], v[4:5], off nt
	s_mul_i32 s15, s20, 0xc00
	s_mul_hi_i32 s13, s20, 0xc00
	s_add_u32 s15, s4, s15
	s_addc_u32 s21, s5, s13
	s_ashr_i32 s13, s12, 31
	s_lshl_b64 s[22:23], s[12:13], 2
	s_add_u32 s22, s15, s22
	s_addc_u32 s23, s21, s23
	s_and_b64 vcc, exec, s[2:3]
	v_lshl_add_u64 v[18:19], s[22:23], 0, v[16:17]
	s_waitcnt vmcnt(1)
	ds_write2_b32 v21, v0, v1 offset1:1
	ds_write2_b32 v22, v2, v3 offset1:1
	s_waitcnt vmcnt(0)
	ds_write2_b32 v23, v4, v5 offset1:1
	ds_write2_b32 v24, v6, v7 offset1:1
	s_waitcnt lgkmcnt(0)
	s_barrier
	ds_read_b32 v0, v25 offset:32768
	s_cbranch_vccnz .LBB0_68
	global_load_dword v1, v[18:19], off nt
	s_waitcnt vmcnt(0) lgkmcnt(0)
	v_mul_f32_e32 v0, v0, v1
.LBB0_68:
	ds_read_b32 v1, v25 offset:33028
	s_and_b64 vcc, exec, s[2:3]
	s_cbranch_vccnz .LBB0_70
	global_load_dword v2, v[18:19], off offset:4 nt
	s_waitcnt vmcnt(0) lgkmcnt(0)
	v_mul_f32_e32 v1, v1, v2
.LBB0_70:
	ds_read_b32 v2, v25 offset:33288
	s_and_b64 vcc, exec, s[2:3]
	s_cbranch_vccnz .LBB0_72
	global_load_dword v3, v[18:19], off offset:8 nt
	s_waitcnt vmcnt(0) lgkmcnt(0)
	v_mul_f32_e32 v2, v2, v3
.LBB0_72:
	ds_read_b32 v3, v25 offset:33548
	s_and_b64 vcc, exec, s[2:3]
	s_cbranch_vccnz .LBB0_74
	global_load_dword v4, v[18:19], off offset:12 nt
	s_waitcnt vmcnt(0) lgkmcnt(0)
	v_mul_f32_e32 v3, v3, v4
.LBB0_74:
	ds_read_b32 v4, v25 offset:33808
	s_and_b64 vcc, exec, s[2:3]
	s_cbranch_vccnz .LBB0_76
	global_load_dword v5, v[18:19], off offset:16 nt
	s_waitcnt vmcnt(0) lgkmcnt(0)
	v_mul_f32_e32 v4, v4, v5
.LBB0_76:
	ds_read_b32 v5, v25 offset:34068
	s_and_b64 vcc, exec, s[2:3]
	s_cbranch_vccnz .LBB0_78
	global_load_dword v6, v[18:19], off offset:20 nt
	s_waitcnt vmcnt(0) lgkmcnt(0)
	v_mul_f32_e32 v5, v5, v6
.LBB0_78:
	ds_read_b32 v6, v25 offset:34328
	s_and_b64 vcc, exec, s[2:3]
	s_cbranch_vccnz .LBB0_80
	global_load_dword v7, v[18:19], off offset:24 nt
	s_waitcnt vmcnt(0) lgkmcnt(0)
	v_mul_f32_e32 v6, v6, v7
.LBB0_80:
	ds_read_b32 v7, v25 offset:34588
	s_and_b64 vcc, exec, s[2:3]
	s_cbranch_vccnz .LBB0_65
	global_load_dword v10, v[18:19], off offset:28 nt
	s_waitcnt vmcnt(0) lgkmcnt(0)
	v_mul_f32_e32 v7, v7, v10
	s_branch .LBB0_65

;     ...
;     for (int it = F.vcu; it < total; it += F.G) {
;         const int mat = it / per, rem = it % per, tn = rem / ntk, tk = rem % ntk, k0 = tk * 64, n0 = tn * 64;
;         const float* s = src + (size_t)mat * K * N; bf16_t* d = dst + (size_t)mat * Npad * K;
;         __syncthreads();
;         { const int r = F.tid >> 4, c4 = (F.tid & 15) * 4;
; #pragma unroll
;           for (int i = 0; i < 2; ++i) { const int rr = r + i * 32; f32x4 v = (f32x4){0.f, 0.f, 0.f, 0.f};
;               const int sn0 = n0 < pad_at ? n0 : n0 - pad_len;
;               if (sn0 + c4 < N && !(n0 >= pad_at && n0 < pad_at + pad_len)) v = *(const f32x4*)(s + (size_t)(k0 + rr) * N + sn0 + c4);
;               tile[rr * 65 + c4 + 0] = v[0]; tile[rr * 65 + c4 + 1] = v[1]; tile[rr * 65 + c4 + 2] = v[2]; tile[rr * 65 + c4 + 3] = v[3]; } }
;         __syncthreads();
;         { const int n = F.tid >> 3, kc = (F.tid & 7) * 8; float v[8];
; #pragma unroll
;           for (int e = 0; e < 8; ++e) { v[e] = tile[(kc + e) * 65 + n]; if (gain) v[e] *= gain[(size_t)mat * K + k0 + kc + e]; }
.LBB0_85:
	s_ashr_i32 s12, s19, 31
	s_lshr_b32 s12, s12, 24
	s_add_i32 s12, s19, s12
	s_ashr_i32 s16, s12, 8
	s_and_b32 s12, s12, 0xff00
	s_sub_i32 s12, s19, s12
	s_sext_i32_i16 s13, s12
	s_bfe_u32 s13, s13, 0x3001c
	s_add_i32 s13, s12, s13
	s_sext_i32_i16 s14, s13
	s_and_b32 s13, s13, 0xfff8
	s_sub_i32 s12, s12, s13
	s_sext_i32_i16 s12, s12
	s_lshl_b32 s13, s14, 3
	s_ashr_i32 s17, s16, 31
	s_lshl_b32 s12, s12, 6
	s_and_b32 s14, s13, 0xffffffc0
	s_lshl_b64 s[20:21], s[16:17], 22
	s_add_u32 s13, s6, s20
	s_addc_u32 s22, s7, s21
	s_ashr_i32 s15, s14, 31
	s_lshl_b64 s[20:21], s[14:15], 2
	s_add_u32 s20, s13, s20
	v_add_u32_e32 v6, s12, v9
	s_addc_u32 s21, s22, s21
	v_ashrrev_i32_e32 v7, 31, v6
	v_lshl_add_u64 v[4:5], s[20:21], 0, v[14:15]
	v_lshlrev_b64 v[0:1], 13, v[6:7]
	v_add_u32_e32 v6, 32, v6
	v_lshl_add_u64 v[0:1], v[4:5], 0, v[0:1]
	v_ashrrev_i32_e32 v7, 31, v6
	s_barrier
	global_load_dwordx4 v[0:3], v[0:1], off nt
	v_lshlrev_b64 v[6:7], 13, v[6:7]
	v_lshl_add_u64 v[4:5], v[4:5], 0, v[6:7]
	global_load_dwordx4 v[4:7], v[4:5], off nt
	s_lshl_b64 s[20:21], s[16:17], 11
	s_add_u32 s15, s4, s20
	s_addc_u32 s22, s5, s21
	s_ashr_i32 s13, s12, 31
	s_lshl_b64 s[20:21], s[12:13], 2
	s_add_u32 s20, s15, s20
	s_addc_u32 s21, s22, s21
	s_and_b64 vcc, exec, s[2:3]
	v_lshl_add_u64 v[18:19], s[20:21], 0, v[16:17]
	s_waitcnt vmcnt(1)
	ds_write2_b32 v21, v0, v1 offset1:1
	ds_write2_b32 v22, v2, v3 offset1:1
	s_waitcnt vmcnt(0)
	ds_write2_b32 v23, v4, v5 offset1:1
	ds_write2_b32 v24, v6, v7 offset1:1
	s_waitcnt lgkmcnt(0)
	s_barrier
	ds_read_b32 v0, v25 offset:32768
	s_cbranch_vccnz .LBB0_87
	global_load_dword v1, v[18:19], off nt
	s_waitcnt vmcnt(0) lgkmcnt(0)
	v_mul_f32_e32 v0, v0, v1

; __device__ __forceinline__ unsigned cvt_pk_bf16(float lo, float hi) { unsigned r; asm("v_cvt_pk_bf16_f32 %0, %1, %2" : "=v"(r) : "v"(lo), "v"(hi)); return r; }
;     ...
;     for (int it = F.vcu; it < total; it += F.G) {
;         const int mat = it / per, rem = it % per, tn = rem / ntk, tk = rem % ntk, k0 = tk * 64, n0 = tn * 64;
;         const float* s = src + (size_t)mat * K * N; bf16_t* d = dst + (size_t)mat * Npad * K;
;         __syncthreads();
;         { const int r = F.tid >> 4, c4 = (F.tid & 15) * 4;
; #pragma unroll
;           for (int i = 0; i < 2; ++i) { const int rr = r + i * 32; f32x4 v = (f32x4){0.f, 0.f, 0.f, 0.f};
;               const int sn0 = n0 < pad_at ? n0 : n0 - pad_len;
;               if (sn0 + c4 < N && !(n0 >= pad_at && n0 < pad_at + pad_len)) v = *(const f32x4*)(s + (size_t)(k0 + rr) * N + sn0 + c4);
;               tile[rr * 65 + c4 + 0] = v[0]; tile[rr * 65 + c4 + 1] = v[1]; tile[rr * 65 + c4 + 2] = v[2]; tile[rr * 65 + c4 + 3] = v[3]; } }
;         __syncthreads();
;         { const int n = F.tid >> 3, kc = (F.tid & 7) * 8; float v[8];
; #pragma unroll
;           for (int e = 0; e < 8; ++e) { v[e] = tile[(kc + e) * 65 + n]; if (gain) v[e] *= gain[(size_t)mat * K + k0 + kc + e]; }
;           u32x4 w; w.x = cvt_pk_bf16(v[0], v[1]); w.y = cvt_pk_bf16(v[2], v[3]); w.z = cvt_pk_bf16(v[4], v[5]); w.w = cvt_pk_bf16(v[6], v[7]);
;           *(u32x4*)(d + (size_t)(n0 + n) * K + k0 + kc) = w; }
.LBB0_103:
	s_ashr_i32 s12, s9, 31
	s_lshr_b32 s12, s12, 22
	s_add_i32 s13, s9, s12
	s_ashr_i32 s12, s13, 10
	s_and_b32 s13, s13, 0xfc00
	s_sub_i32 s16, s9, s13
	s_sext_i32_i16 s17, s16
	s_bfe_u32 s17, s17, 0x5001a
	s_add_i32 s17, s16, s17
	s_sext_i32_i16 s18, s17
	s_and_b32 s17, s17, 0xffe0
	s_sub_i32 s16, s16, s17
	s_ashr_i32 s13, s12, 31
	s_lshl_b32 s17, s18, 1
	s_sext_i32_i16 s18, s16
	s_lshl_b64 s[14:15], s[12:13], 24
	s_and_b32 s16, s17, 0xffffffc0
	s_lshl_b32 s18, s18, 6
	s_waitcnt lgkmcnt(0)
	s_add_u32 s19, s4, s14
	s_addc_u32 s20, s5, s15
	s_ashr_i32 s17, s16, 31
	s_lshl_b64 s[14:15], s[16:17], 2
	v_add_u32_e32 v14, s18, v9
	s_add_u32 s14, s19, s14
	v_ashrrev_i32_e32 v15, 31, v14
	v_add_u32_e32 v16, 32, v14
	s_addc_u32 s15, s20, s15
	v_lshlrev_b64 v[14:15], 13, v[14:15]
	v_ashrrev_i32_e32 v17, 31, v16
	v_lshl_add_u64 v[18:19], s[14:15], 0, v[0:1]
	v_lshlrev_b64 v[16:17], 13, v[16:17]
	v_lshl_add_u64 v[26:27], v[18:19], 0, v[14:15]
	s_barrier
	v_lshl_add_u64 v[18:19], v[18:19], 0, v[16:17]
	global_load_dwordx4 v[14:17], v[26:27], off nt
	global_load_dwordx4 v[22:25], v[18:19], off nt
	v_add_u32_e32 v18, s16, v13
	s_ashr_i32 s19, s18, 31
	s_lshl_b64 s[12:13], s[12:13], 23
	v_ashrrev_i32_e32 v19, 31, v18
	s_add_u32 s12, s6, s12
	v_lshlrev_b64 v[18:19], 12, v[18:19]
	s_addc_u32 s13, s7, s13
	v_lshl_add_u64 v[18:19], s[12:13], 0, v[18:19]
	s_add_i32 s9, s9, s8
	v_lshl_add_u64 v[18:19], s[18:19], 1, v[18:19]
	s_cmpk_lt_i32 s9, 0x800
	v_lshl_add_u64 v[18:19], v[18:19], 0, v[2:3]
	s_waitcnt vmcnt(1)
	ds_write2_b32 v4, v14, v15 offset1:1
	ds_write2_b32 v5, v16, v17 offset1:1
	s_waitcnt vmcnt(0)
	ds_write2_b32 v6, v22, v23 offset1:1
	ds_write2_b32 v7, v24, v25 offset1:1
	s_waitcnt lgkmcnt(0)
	s_barrier
	ds_read2_b32 v[14:15], v10 offset1:65
	ds_read2_b32 v[16:17], v10 offset0:130 offset1:195
	ds_read2_b32 v[22:23], v11 offset0:4 offset1:69
	ds_read2_b32 v[24:25], v11 offset0:134 offset1:199
	s_waitcnt lgkmcnt(3)
	v_cvt_pk_bf16_f32 v14, v14, v15
	s_waitcnt lgkmcnt(2)
	v_cvt_pk_bf16_f32 v15, v16, v17
	s_waitcnt lgkmcnt(1)
	v_cvt_pk_bf16_f32 v16, v22, v23
	s_waitcnt lgkmcnt(0)
	v_cvt_pk_bf16_f32 v17, v24, v25
	global_store_dwordx4 v[18:19], v[14:17], off
	s_cbranch_scc1 .LBB0_103

; __device__ __forceinline__ unsigned cvt_pk_bf16(float lo, float hi) { unsigned r; asm("v_cvt_pk_bf16_f32 %0, %1, %2" : "=v"(r) : "v"(lo), "v"(hi)); return r; }
;     ...
;     for (int it = F.vcu; it < total; it += F.G) {
;         const int mat = it / per, rem = it % per, tn = rem / ntk, tk = rem % ntk, k0 = tk * 64, n0 = tn * 64;
;         const float* s = src + (size_t)mat * K * N; bf16_t* d = dst + (size_t)mat * Npad * K;
;         __syncthreads();
;         { const int r = F.tid >> 4, c4 = (F.tid & 15) * 4;
; #pragma unroll
;           for (int i = 0; i < 2; ++i) { const int rr = r + i * 32; f32x4 v = (f32x4){0.f, 0.f, 0.f, 0.f};
;               const int sn0 = n0 < pad_at ? n0 : n0 - pad_len;
;               if (sn0 + c4 < N && !(n0 >= pad_at && n0 < pad_at + pad_len)) v = *(const f32x4*)(s + (size_t)(k0 + rr) * N + sn0 + c4);
;               tile[rr * 65 + c4 + 0] = v[0]; tile[rr * 65 + c4 + 1] = v[1]; tile[rr * 65 + c4 + 2] = v[2]; tile[rr * 65 + c4 + 3] = v[3]; } }
;         __syncthreads();
;         { const int n = F.tid >> 3, kc = (F.tid & 7) * 8; float v[8];
; #pragma unroll
;           for (int e = 0; e < 8; ++e) { v[e] = tile[(kc + e) * 65 + n]; if (gain) v[e] *= gain[(size_t)mat * K + k0 + kc + e]; }
;           u32x4 w; w.x = cvt_pk_bf16(v[0], v[1]); w.y = cvt_pk_bf16(v[2], v[3]); w.z = cvt_pk_bf16(v[4], v[5]); w.w = cvt_pk_bf16(v[6], v[7]);
;           *(u32x4*)(d + (size_t)(n0 + n) * K + k0 + kc) = w; }
.LBB0_106:
	s_mul_hi_i32 s13, s12, 0x2aaaaaab
	s_lshr_b32 s14, s13, 31
	s_ashr_i32 s13, s13, 8
	s_add_i32 s13, s13, s14
	s_mul_i32 s14, s13, 0xfffffa00
	s_add_i32 s14, s12, s14
	s_bfe_u32 s16, s14, 0x5001a
	s_add_i32 s16, s14, s16
	s_sext_i32_i16 s18, s16
	s_and_b32 s16, s16, 0xffe0
	s_sub_i32 s14, s14, s16
	s_lshl_b32 s16, s18, 1
	s_sext_i32_i16 s18, s14
	s_mul_i32 s17, s13, 0x1800000
	s_and_b32 s14, s16, 0xffffffc0
	s_lshl_b32 s16, s18, 6
	s_mul_hi_i32 s15, s13, 0x1800000
	s_waitcnt lgkmcnt(0)
	s_add_u32 s17, s4, s17
	s_addc_u32 s20, s5, s15
	s_ashr_i32 s15, s14, 31
	s_lshl_b64 s[18:19], s[14:15], 2
	s_add_u32 s18, s17, s18
	s_addc_u32 s19, s20, s19
	v_add_u32_e32 v12, s16, v9
	v_lshl_add_u64 v[14:15], s[18:19], 0, v[0:1]
	v_add_u32_e32 v16, 32, v12
	v_mad_i64_i32 v[18:19], s[18:19], v12, s9, v[14:15]
	s_barrier
	v_mad_i64_i32 v[26:27], s[18:19], v16, s9, v[14:15]
	global_load_dwordx4 v[14:17], v[18:19], off nt
	global_load_dwordx4 v[22:25], v[26:27], off nt
	s_mul_hi_i32 s15, s13, 0xc00000
	s_mul_i32 s13, s13, 0xc00000
	v_add_u32_e32 v18, s14, v13
	s_ashr_i32 s17, s16, 31
	v_ashrrev_i32_e32 v19, 31, v18
	s_add_u32 s14, s6, s13
	v_lshlrev_b64 v[18:19], 12, v[18:19]
	s_addc_u32 s15, s7, s15
	v_lshl_add_u64 v[18:19], s[14:15], 0, v[18:19]
	s_add_i32 s12, s12, s8
	v_lshl_add_u64 v[18:19], s[16:17], 1, v[18:19]
	s_cmpk_lt_i32 s12, 0xc00
	v_lshl_add_u64 v[18:19], v[18:19], 0, v[2:3]
	s_waitcnt vmcnt(1)
	ds_write2_b32 v4, v14, v15 offset1:1
	ds_write2_b32 v5, v16, v17 offset1:1
	s_waitcnt vmcnt(0)
	ds_write2_b32 v6, v22, v23 offset1:1
	ds_write2_b32 v7, v24, v25 offset1:1
	s_waitcnt lgkmcnt(0)
	s_barrier
	ds_read2_b32 v[14:15], v10 offset1:65
	ds_read2_b32 v[16:17], v10 offset0:130 offset1:195
	ds_read2_b32 v[22:23], v11 offset0:4 offset1:69
	ds_read2_b32 v[24:25], v11 offset0:134 offset1:199
	s_waitcnt lgkmcnt(3)
	v_cvt_pk_bf16_f32 v14, v14, v15
	s_waitcnt lgkmcnt(2)
	v_cvt_pk_bf16_f32 v15, v16, v17
	s_waitcnt lgkmcnt(1)
	v_cvt_pk_bf16_f32 v16, v22, v23
	s_waitcnt lgkmcnt(0)
	v_cvt_pk_bf16_f32 v17, v24, v25
	global_store_dwordx4 v[18:19], v[14:17], off
	s_cbranch_scc1 .LBB0_106

; __device__ __forceinline__ unsigned cvt_pk_bf16(float lo, float hi) { unsigned r; asm("v_cvt_pk_bf16_f32 %0, %1, %2" : "=v"(r) : "v"(lo), "v"(hi)); return r; }
;     ...
;     for (int it = F.vcu; it < total; it += F.G) {
;         const int mat = it / per, rem = it % per, tn = rem / ntk, tk = rem % ntk, k0 = tk * 64, n0 = tn * 64;
;         const float* s = src + (size_t)mat * K * N; bf16_t* d = dst + (size_t)mat * Npad * K;
;         __syncthreads();
;         { const int r = F.tid >> 4, c4 = (F.tid & 15) * 4;
; #pragma unroll
;           for (int i = 0; i < 2; ++i) { const int rr = r + i * 32; f32x4 v = (f32x4){0.f, 0.f, 0.f, 0.f};
;               const int sn0 = n0 < pad_at ? n0 : n0 - pad_len;
;               if (sn0 + c4 < N && !(n0 >= pad_at && n0 < pad_at + pad_len)) v = *(const f32x4*)(s + (size_t)(k0 + rr) * N + sn0 + c4);
;               tile[rr * 65 + c4 + 0] = v[0]; tile[rr * 65 + c4 + 1] = v[1]; tile[rr * 65 + c4 + 2] = v[2]; tile[rr * 65 + c4 + 3] = v[3]; } }
;         __syncthreads();
;         { const int n = F.tid >> 3, kc = (F.tid & 7) * 8; float v[8];
; #pragma unroll
;           for (int e = 0; e < 8; ++e) { v[e] = tile[(kc + e) * 65 + n]; if (gain) v[e] *= gain[(size_t)mat * K + k0 + kc + e]; }
;           u32x4 w; w.x = cvt_pk_bf16(v[0], v[1]); w.y = cvt_pk_bf16(v[2], v[3]); w.z = cvt_pk_bf16(v[4], v[5]); w.w = cvt_pk_bf16(v[6], v[7]);
;           *(u32x4*)(d + (size_t)(n0 + n) * K + k0 + kc) = w; }
.LBB0_109:
	s_ashr_i32 s7, s6, 31
	s_lshr_b32 s7, s7, 22
	s_add_i32 s7, s6, s7
	s_ashr_i32 s12, s7, 10
	s_and_b32 s7, s7, 0xfc00
	s_sub_i32 s7, s6, s7
	s_sext_i32_i16 s9, s7
	s_bfe_u32 s9, s9, 0x5001a
	s_add_i32 s9, s7, s9
	s_sext_i32_i16 s16, s9
	s_and_b32 s9, s9, 0xffe0
	s_sub_i32 s7, s7, s9
	s_ashr_i32 s13, s12, 31
	s_lshl_b32 s9, s16, 1
	s_sext_i32_i16 s7, s7
	s_lshl_b64 s[14:15], s[12:13], 24
	s_and_b32 s16, s9, 0xffffffc0
	s_lshl_b32 s18, s7, 6
	s_waitcnt lgkmcnt(0)
	s_add_u32 s7, s2, s14
	s_addc_u32 s9, s3, s15
	s_ashr_i32 s17, s16, 31
	s_lshl_b64 s[14:15], s[16:17], 2
	v_add_u32_e32 v14, s18, v9
	s_add_u32 s14, s7, s14
	v_ashrrev_i32_e32 v15, 31, v14
	v_add_u32_e32 v16, 32, v14
	s_addc_u32 s15, s9, s15
	v_lshlrev_b64 v[14:15], 13, v[14:15]
	v_ashrrev_i32_e32 v17, 31, v16
	v_lshl_add_u64 v[18:19], s[14:15], 0, v[0:1]
	v_lshlrev_b64 v[16:17], 13, v[16:17]
	v_lshl_add_u64 v[26:27], v[18:19], 0, v[14:15]
	s_barrier
	v_lshl_add_u64 v[18:19], v[18:19], 0, v[16:17]
	global_load_dwordx4 v[14:17], v[26:27], off nt
	global_load_dwordx4 v[22:25], v[18:19], off nt
	v_add_u32_e32 v18, s16, v13
	s_ashr_i32 s19, s18, 31
	s_lshl_b64 s[12:13], s[12:13], 23
	v_ashrrev_i32_e32 v19, 31, v18
	s_add_u32 s12, s4, s12
	v_lshlrev_b64 v[18:19], 12, v[18:19]
	s_addc_u32 s13, s5, s13
	v_lshl_add_u64 v[18:19], s[12:13], 0, v[18:19]
	s_add_i32 s6, s6, s8
	v_lshl_add_u64 v[18:19], s[18:19], 1, v[18:19]
	s_cmpk_lt_i32 s6, 0x800
	v_lshl_add_u64 v[18:19], v[18:19], 0, v[2:3]
	s_waitcnt vmcnt(1)
	ds_write2_b32 v4, v14, v15 offset1:1
	ds_write2_b32 v5, v16, v17 offset1:1
	s_waitcnt vmcnt(0)
	ds_write2_b32 v6, v22, v23 offset1:1
	ds_write2_b32 v7, v24, v25 offset1:1
	s_waitcnt lgkmcnt(0)
	s_barrier
	ds_read2_b32 v[14:15], v10 offset1:65
	ds_read2_b32 v[16:17], v10 offset0:130 offset1:195
	ds_read2_b32 v[22:23], v11 offset0:4 offset1:69
	ds_read2_b32 v[24:25], v11 offset0:134 offset1:199
	s_waitcnt lgkmcnt(3)
	v_cvt_pk_bf16_f32 v14, v14, v15
	s_waitcnt lgkmcnt(2)
	v_cvt_pk_bf16_f32 v15, v16, v17
	s_waitcnt lgkmcnt(1)
	v_cvt_pk_bf16_f32 v16, v22, v23
	s_waitcnt lgkmcnt(0)
	v_cvt_pk_bf16_f32 v17, v24, v25
	global_store_dwordx4 v[18:19], v[14:17], off
	s_cbranch_scc1 .LBB0_109

; __device__ __forceinline__ unsigned cvt_pk_bf16(float lo, float hi) { unsigned r; asm("v_cvt_pk_bf16_f32 %0, %1, %2" : "=v"(r) : "v"(lo), "v"(hi)); return r; }
;     ...
;     for (int it = F.vcu; it < total; it += F.G) {
;         const int mat = it / per, rem = it % per, tn = rem / ntk, tk = rem % ntk, k0 = tk * 64, n0 = tn * 64;
;         const float* s = src + (size_t)mat * K * N; bf16_t* d = dst + (size_t)mat * Npad * K;
;         __syncthreads();
;         { const int r = F.tid >> 4, c4 = (F.tid & 15) * 4;
; #pragma unroll
;           for (int i = 0; i < 2; ++i) { const int rr = r + i * 32; f32x4 v = (f32x4){0.f, 0.f, 0.f, 0.f};
;               const int sn0 = n0 < pad_at ? n0 : n0 - pad_len;
;               if (sn0 + c4 < N && !(n0 >= pad_at && n0 < pad_at + pad_len)) v = *(const f32x4*)(s + (size_t)(k0 + rr) * N + sn0 + c4);
;               tile[rr * 65 + c4 + 0] = v[0]; tile[rr * 65 + c4 + 1] = v[1]; tile[rr * 65 + c4 + 2] = v[2]; tile[rr * 65 + c4 + 3] = v[3]; } }
;         __syncthreads();
;         { const int n = F.tid >> 3, kc = (F.tid & 7) * 8; float v[8];
; #pragma unroll
;           for (int e = 0; e < 8; ++e) { v[e] = tile[(kc + e) * 65 + n]; if (gain) v[e] *= gain[(size_t)mat * K + k0 + kc + e]; }
;           u32x4 w; w.x = cvt_pk_bf16(v[0], v[1]); w.y = cvt_pk_bf16(v[2], v[3]); w.z = cvt_pk_bf16(v[4], v[5]); w.w = cvt_pk_bf16(v[6], v[7]);
;           *(u32x4*)(d + (size_t)(n0 + n) * K + k0 + kc) = w; }
.LBB0_112:
	s_ashr_i32 s7, s6, 31
	s_lshr_b32 s7, s7, 22
	s_add_i32 s7, s6, s7
	s_ashr_i32 s12, s7, 10
	s_and_b32 s7, s7, 0xfc00
	s_sub_i32 s7, s6, s7
	s_sext_i32_i16 s9, s7
	s_bfe_u32 s9, s9, 0x5001a
	s_add_i32 s9, s7, s9
	s_sext_i32_i16 s16, s9
	s_and_b32 s9, s9, 0xffe0
	s_sub_i32 s7, s7, s9
	s_ashr_i32 s13, s12, 31
	s_lshl_b32 s9, s16, 1
	s_sext_i32_i16 s7, s7
	s_lshl_b64 s[14:15], s[12:13], 24
	s_and_b32 s16, s9, 0xffffffc0
	s_lshl_b32 s18, s7, 6
	s_waitcnt lgkmcnt(0)
	s_add_u32 s7, s2, s14
	s_addc_u32 s9, s3, s15
	s_ashr_i32 s17, s16, 31
	s_lshl_b64 s[14:15], s[16:17], 2
	v_add_u32_e32 v14, s18, v9
	s_add_u32 s14, s7, s14
	v_ashrrev_i32_e32 v15, 31, v14
	v_add_u32_e32 v16, 32, v14
	s_addc_u32 s15, s9, s15
	v_lshlrev_b64 v[14:15], 13, v[14:15]
	v_ashrrev_i32_e32 v17, 31, v16
	v_lshl_add_u64 v[18:19], s[14:15], 0, v[0:1]
	v_lshlrev_b64 v[16:17], 13, v[16:17]
	v_lshl_add_u64 v[22:23], v[18:19], 0, v[14:15]
	s_barrier
	v_lshl_add_u64 v[24:25], v[18:19], 0, v[16:17]
	global_load_dwordx4 v[14:17], v[22:23], off nt
	global_load_dwordx4 v[18:21], v[24:25], off nt
	v_add_u32_e32 v22, s16, v13
	s_ashr_i32 s19, s18, 31
	s_lshl_b64 s[12:13], s[12:13], 23
	v_ashrrev_i32_e32 v23, 31, v22
	s_add_u32 s12, s4, s12
	v_lshlrev_b64 v[22:23], 12, v[22:23]
	s_addc_u32 s13, s5, s13
	v_lshl_add_u64 v[22:23], s[12:13], 0, v[22:23]
	s_add_i32 s6, s6, s8
	v_lshl_add_u64 v[22:23], s[18:19], 1, v[22:23]
	s_cmpk_lt_i32 s6, 0x1000
	v_lshl_add_u64 v[22:23], v[22:23], 0, v[2:3]
	s_waitcnt vmcnt(1)
	ds_write2_b32 v4, v14, v15 offset1:1
	ds_write2_b32 v5, v16, v17 offset1:1
	s_waitcnt vmcnt(0)
	ds_write2_b32 v6, v18, v19 offset1:1
	ds_write2_b32 v7, v20, v21 offset1:1
	s_waitcnt lgkmcnt(0)
	s_barrier
	ds_read2_b32 v[14:15], v10 offset1:65
	ds_read2_b32 v[16:17], v10 offset0:130 offset1:195
	ds_read2_b32 v[18:19], v11 offset0:4 offset1:69
	ds_read2_b32 v[20:21], v11 offset0:134 offset1:199
	s_waitcnt lgkmcnt(3)
	v_cvt_pk_bf16_f32 v14, v14, v15
	s_waitcnt lgkmcnt(2)
	v_cvt_pk_bf16_f32 v15, v16, v17
	s_waitcnt lgkmcnt(1)
	v_cvt_pk_bf16_f32 v16, v18, v19
	s_waitcnt lgkmcnt(0)
	v_cvt_pk_bf16_f32 v17, v20, v21
	global_store_dwordx4 v[22:23], v[14:17], off
	s_cbranch_scc1 .LBB0_112

; __device__ __forceinline__ unsigned cvt_pk_bf16(float lo, float hi) { unsigned r; asm("v_cvt_pk_bf16_f32 %0, %1, %2" : "=v"(r) : "v"(lo), "v"(hi)); return r; }
; __device__ __forceinline__ void cvt_flat(const Ctx& F, const float* src, bf16_t* dst, size_t n8) {
;     for (size_t i = (size_t)F.vcu * 512 + F.tid; i < n8; i += (size_t)F.G * 512) {
;         const f32x4 a = *(const f32x4*)(src + i * 8), b = *(const f32x4*)(src + i * 8 + 4);
;         u32x4 w; w.x = cvt_pk_bf16(a[0], a[1]); w.y = cvt_pk_bf16(a[2], a[3]); w.z = cvt_pk_bf16(b[0], b[1]); w.w = cvt_pk_bf16(b[2], b[3]);
;         *(u32x4*)(dst + i * 8) = w;
;     }
; }
.LBB0_115:
	global_load_dwordx4 v[6:9], v[4:5], off offset:-16 nt
	global_load_dwordx4 v[10:13], v[4:5], off nt
	v_lshl_add_u64 v[0:1], v[0:1], 0, s[4:5]
	v_cmp_lt_u64_e32 vcc, s[16:17], v[0:1]
	v_lshl_add_u64 v[4:5], v[4:5], 0, s[12:13]
	s_or_b64 s[14:15], vcc, s[14:15]
	s_waitcnt vmcnt(1)
	v_cvt_pk_bf16_f32 v6, v6, v7
	v_cvt_pk_bf16_f32 v7, v8, v9
	s_waitcnt vmcnt(0)
	v_cvt_pk_bf16_f32 v8, v10, v11
	v_cvt_pk_bf16_f32 v9, v12, v13
	global_store_dwordx4 v[2:3], v[6:9], off
	v_lshl_add_u64 v[2:3], v[2:3], 0, s[6:7]
	s_andn2_b64 exec, exec, s[14:15]
	s_cbranch_execnz .LBB0_115

; __device__ __forceinline__ void cvt_rows_fp6(const Ctx& F, const float* src, unsigned char* dst, float* descale, int R) {
;     ...
;     for (int row = F.vcu * 8 + F.wid; row < R; row += F.G * 8) {
;         const float* s = src + (size_t)row * DM + F.lane * 4; f32x4 v[8]; float am = 0.f;
; #pragma unroll
;         for (int i = 0; i < 8; ++i) { v[i] = *(const f32x4*)(s + i * 256);
; #pragma unroll
;             for (int e = 0; e < 4; ++e) am = fmaxf(am, fabsf(v[i][e])); }
;         am = wave_max(am);
;         const float sc = am > 0.f ? 7.f / am : 1.f;
; #pragma unroll
;         for (int i = 0; i < 8; ++i)
; #pragma unroll
;             for (int e = 0; e < 4; ++e) stg[F.lane * 33 + permL[i * 4 + e]] = v[i][e] * sc;
;         asm volatile("s_waitcnt lgkmcnt(0)" ::: "memory"); __builtin_amdgcn_wave_barrier(); asm volatile("" ::: "memory");
;         v16f lo, hi;
; #pragma unroll
;         for (int i = 0; i < 16; ++i) { lo[i] = stg[F.lane * 33 + i]; hi[i] = stg[F.lane * 33 + 16 + i]; }
;         asm volatile("s_waitcnt lgkmcnt(0)" ::: "memory"); __builtin_amdgcn_wave_barrier(); asm volatile("" ::: "memory");
;         const v6u w = __builtin_amdgcn_cvt_scalef32_2xpk16_fp6_f32(lo, hi, 1.0f);
;         unsigned char* d = dst + (size_t)row * EROW;
;         *(u32x4*)(d + F.lane * 16) = (u32x4){w[0], w[1], w[2], w[3]}; *(u32x2*)(d + 1024 + F.lane * 8) = (u32x2){w[4], w[5]};
.LBB0_537:
	global_load_dwordx4 v[52:55], v[74:75], off offset:-4096 nt
	global_load_dwordx4 v[48:51], v[74:75], off offset:-3072 nt
	global_load_dwordx4 v[44:47], v[74:75], off offset:-2048 nt
	global_load_dwordx4 v[40:43], v[74:75], off offset:-1024 nt
	global_load_dwordx4 v[36:39], v[74:75], off nt
	global_load_dwordx4 v[32:35], v[74:75], off offset:1024 nt
	global_load_dwordx4 v[56:59], v[74:75], off offset:2048 nt
	global_load_dwordx4 v[60:63], v[74:75], off offset:3072 nt
	ds_read_b128 v[80:83], v67
	ds_read_b128 v[84:87], v67 offset:16
	ds_read_b128 v[88:91], v67 offset:32
	ds_read_b128 v[92:95], v67 offset:48
	ds_read_b128 v[96:99], v67 offset:64
	ds_read_b128 v[100:103], v67 offset:80
	ds_read_b128 v[104:107], v67 offset:96
	ds_read_b128 v[108:111], v67 offset:112
	s_waitcnt lgkmcnt(7)
	v_lshl_add_u32 v80, v80, 2, v78
	v_lshl_add_u32 v81, v81, 2, v78
	v_lshl_add_u32 v82, v82, 2, v78
	v_lshl_add_u32 v83, v83, 2, v78
	s_waitcnt lgkmcnt(6)
	v_lshl_add_u32 v84, v84, 2, v78
	v_lshl_add_u32 v85, v85, 2, v78
	v_lshl_add_u32 v86, v86, 2, v78
	v_lshl_add_u32 v87, v87, 2, v78
	s_waitcnt lgkmcnt(5)
	v_lshl_add_u32 v88, v88, 2, v78
	v_lshl_add_u32 v89, v89, 2, v78
	v_lshl_add_u32 v90, v90, 2, v78
	v_lshl_add_u32 v91, v91, 2, v78
	s_waitcnt lgkmcnt(4)
	v_lshl_add_u32 v92, v92, 2, v78
	v_lshl_add_u32 v93, v93, 2, v78
	v_lshl_add_u32 v94, v94, 2, v78
	v_lshl_add_u32 v95, v95, 2, v78
	s_waitcnt lgkmcnt(3)
	v_lshl_add_u32 v96, v96, 2, v78
	v_lshl_add_u32 v97, v97, 2, v78
	v_lshl_add_u32 v98, v98, 2, v78
	v_lshl_add_u32 v99, v99, 2, v78
	s_waitcnt lgkmcnt(2)
	v_lshl_add_u32 v100, v100, 2, v78
	v_lshl_add_u32 v101, v101, 2, v78
	v_lshl_add_u32 v102, v102, 2, v78
	v_lshl_add_u32 v103, v103, 2, v78
	s_waitcnt lgkmcnt(1)
	v_lshl_add_u32 v104, v104, 2, v78
	v_lshl_add_u32 v105, v105, 2, v78
	v_lshl_add_u32 v106, v106, 2, v78
	s_waitcnt vmcnt(7)
	v_max3_f32 v79, |v52|, 0, |v53|
	v_max3_f32 v79, v79, |v54|, |v55|
	s_waitcnt vmcnt(6)
	v_max3_f32 v79, v79, |v48|, |v49|
	v_max3_f32 v79, v79, |v50|, |v51|
	s_waitcnt vmcnt(5)
	v_max3_f32 v79, v79, |v44|, |v45|
	v_max3_f32 v79, v79, |v46|, |v47|
	s_waitcnt vmcnt(4)
	v_max3_f32 v79, v79, |v40|, |v41|
	v_max3_f32 v79, v79, |v42|, |v43|
	s_waitcnt vmcnt(3)
	v_max3_f32 v79, v79, |v36|, |v37|
	v_max3_f32 v79, v79, |v38|, |v39|
	s_waitcnt vmcnt(2)
	v_max3_f32 v79, v79, |v32|, |v33|
	v_max3_f32 v79, v79, |v34|, |v35|
	s_waitcnt vmcnt(1)
	v_max3_f32 v79, v79, |v56|, |v57|
	v_max3_f32 v79, v79, |v58|, |v59|
	s_waitcnt vmcnt(0)
	v_max3_f32 v79, v79, |v60|, |v61|
	v_max3_f32 v79, v79, |v62|, |v63|
	ds_swizzle_b32 v112, v79 offset:swizzle(SWAP,16)
	s_waitcnt lgkmcnt(0)
	v_max_f32_e32 v112, v112, v112
	v_max_f32_e32 v79, v79, v112
	ds_swizzle_b32 v112, v79 offset:swizzle(SWAP,8)
	s_waitcnt lgkmcnt(0)
	v_max_f32_e32 v112, v112, v112
	v_max_f32_e32 v79, v79, v112
	ds_swizzle_b32 v112, v79 offset:swizzle(SWAP,4)
	s_waitcnt lgkmcnt(0)
	v_max_f32_e32 v112, v112, v112
	v_max_f32_e32 v79, v79, v112
	ds_swizzle_b32 v112, v79 offset:swizzle(SWAP,2)
	s_waitcnt lgkmcnt(0)
	v_max_f32_e32 v112, v112, v112
	v_max_f32_e32 v79, v79, v112
	ds_swizzle_b32 v112, v79 offset:swizzle(SWAP,1)
	s_waitcnt lgkmcnt(0)
	v_max_f32_e32 v112, v112, v112
	v_max_f32_e32 v79, v79, v112
	v_mov_b32_e32 v112, v79
	s_nop 1
	v_permlane32_swap_b32_e32 v79, v112
	v_max_f32_e32 v112, v112, v112
	v_max_f32_e32 v79, v79, v79
	v_max_f32_e32 v79, v79, v112
	v_div_scale_f32 v112, s[22:23], v79, v79, s7
	v_rcp_f32_e32 v113, v112
	v_div_scale_f32 v114, vcc, s7, v79, s7
	v_fma_f32 v115, -v112, v113, 1.0
	v_fmac_f32_e32 v113, v115, v113
	v_mul_f32_e32 v115, v114, v113
	v_fma_f32 v116, -v112, v115, v114
	v_fmac_f32_e32 v115, v116, v113
	v_fma_f32 v112, -v112, v115, v114
	v_div_fmas_f32 v112, v112, v113, v115
	v_div_fixup_f32 v112, v112, v79, s7
	v_cmp_lt_f32_e32 vcc, 0, v79
	s_nop 1
	v_cndmask_b32_e32 v112, 1.0, v112, vcc
	v_mul_f32_e32 v52, v52, v112
	v_mul_f32_e32 v32, v32, v112
	v_mul_f32_e32 v53, v53, v112
	v_mul_f32_e32 v54, v54, v112
	v_mul_f32_e32 v55, v55, v112
	v_mul_f32_e32 v48, v48, v112
	v_mul_f32_e32 v49, v49, v112
	v_mul_f32_e32 v50, v50, v112
	v_mul_f32_e32 v51, v51, v112
	v_mul_f32_e32 v44, v44, v112
	v_mul_f32_e32 v45, v45, v112
	v_mul_f32_e32 v46, v46, v112
	v_mul_f32_e32 v47, v47, v112
	v_mul_f32_e32 v40, v40, v112
	v_mul_f32_e32 v41, v41, v112
	v_mul_f32_e32 v42, v42, v112
	v_mul_f32_e32 v43, v43, v112
	v_mul_f32_e32 v36, v36, v112
	v_mul_f32_e32 v37, v37, v112
	v_mul_f32_e32 v38, v38, v112
	v_mul_f32_e32 v39, v39, v112
	v_mul_f32_e32 v33, v33, v112
	v_mul_f32_e32 v34, v34, v112
	v_mul_f32_e32 v35, v35, v112
	v_mul_f32_e32 v56, v56, v112
	v_mul_f32_e32 v57, v57, v112
	v_mul_f32_e32 v58, v58, v112
	v_mul_f32_e32 v59, v59, v112
	ds_write_b32 v80, v52
	ds_write_b32 v81, v53
	ds_write_b32 v82, v54
	ds_write_b32 v83, v55
	ds_write_b32 v84, v48
	ds_write_b32 v85, v49
	ds_write_b32 v86, v50
	ds_write_b32 v87, v51
	ds_write_b32 v88, v44
	ds_write_b32 v89, v45
	ds_write_b32 v90, v46
	ds_write_b32 v91, v47
	ds_write_b32 v92, v40
	ds_write_b32 v93, v41
	ds_write_b32 v94, v42
	ds_write_b32 v95, v43
	ds_write_b32 v96, v36
	ds_write_b32 v97, v37
	ds_write_b32 v98, v38
	ds_write_b32 v99, v39
	ds_write_b32 v100, v32
	ds_write_b32 v101, v33
	ds_write_b32 v102, v34
	ds_write_b32 v103, v35
	ds_write_b32 v104, v56
	ds_write_b32 v105, v57
	ds_write_b32 v106, v58
	v_lshl_add_u32 v32, v107, 2, v78
	ds_write_b32 v32, v59
	v_mul_f32_e32 v32, v60, v112
	v_lshl_add_u32 v34, v108, 2, v78
	v_mul_f32_e32 v33, v61, v112
	ds_write_b32 v34, v32
	v_lshl_add_u32 v32, v109, 2, v78
	ds_write_b32 v32, v33
	v_mul_f32_e32 v32, v62, v112
	v_lshl_add_u32 v34, v110, 2, v78
	v_mul_f32_e32 v33, v63, v112
	ds_write_b32 v34, v32
	v_lshl_add_u32 v32, v111, 2, v78
	ds_write_b32 v32, v33
	s_waitcnt lgkmcnt(0)
	ds_read2_b32 v[32:33], v78 offset1:1
	ds_read2_b32 v[34:35], v78 offset0:2 offset1:3
	ds_read2_b32 v[36:37], v78 offset0:4 offset1:5
	ds_read2_b32 v[38:39], v78 offset0:6 offset1:7
	ds_read2_b32 v[48:49], v78 offset0:16 offset1:17
	ds_read2_b32 v[50:51], v78 offset0:18 offset1:19
	ds_read2_b32 v[52:53], v78 offset0:20 offset1:21
	ds_read2_b32 v[54:55], v78 offset0:22 offset1:23
	ds_read2_b32 v[40:41], v78 offset0:8 offset1:9
	ds_read2_b32 v[42:43], v78 offset0:10 offset1:11
	ds_read2_b32 v[44:45], v78 offset0:12 offset1:13
	ds_read2_b32 v[46:47], v78 offset0:14 offset1:15
	ds_read2_b32 v[56:57], v78 offset0:24 offset1:25
	ds_read2_b32 v[58:59], v78 offset0:26 offset1:27
	ds_read2_b32 v[60:61], v78 offset0:28 offset1:29
	ds_read2_b32 v[62:63], v78 offset0:30 offset1:31
	s_waitcnt lgkmcnt(0)
	s_waitcnt lgkmcnt(0)
	v_cvt_scalef32_2xpk16_fp6_f32 v[32:37], v[32:47], v[48:63], 1.0
	global_store_dwordx4 v[72:73], v[32:35], off
	s_nop 1
	v_lshl_add_u64 v[32:33], v[72:73], 0, v[70:71]
	global_store_dwordx2 v[32:33], v[36:37], off offset:1024
	s_and_saveexec_b64 s[22:23], s[2:3]
	s_cbranch_execz .LBB0_536
; __device__ __forceinline__ void cvt_rows_fp6(const Ctx& F, const float* src, unsigned char* dst, float* descale, int R) {
;     ...
;         if (F.lane == 0) descale[row] = (am > 0.f ? am * (1.f / 7.f) : 1.f) / (fac > 0.f ? fac : 1.f);
	v_mul_f32_e32 v32, 0x3e124925, v79
	v_cndmask_b32_e32 v32, 1.0, v32, vcc
	v_div_scale_f32 v33, s[30:31], v77, v77, v32
	v_rcp_f32_e32 v34, v33
	v_div_scale_f32 v35, vcc, v32, v77, v32
	v_fma_f32 v36, -v33, v34, 1.0
	v_fmac_f32_e32 v34, v36, v34
	v_mul_f32_e32 v36, v35, v34
	v_fma_f32 v37, -v33, v36, v35
	v_fmac_f32_e32 v36, v37, v34
	v_fma_f32 v33, -v33, v36, v35
	v_div_fmas_f32 v33, v33, v34, v36
	v_div_fixup_f32 v32, v33, v77, v32
	global_store_dword v69, v32, s[14:15]
	s_branch .LBB0_536

; __device__ __forceinline__ void cvt_rows_fp6(const Ctx& F, const float* src, unsigned char* dst, float* descale, int R) {
;     ...
;     for (int row = F.vcu * 8 + F.wid; row < R; row += F.G * 8) {
;         const float* s = src + (size_t)row * DM + F.lane * 4; f32x4 v[8]; float am = 0.f;
; #pragma unroll
;         for (int i = 0; i < 8; ++i) { v[i] = *(const f32x4*)(s + i * 256);
; #pragma unroll
;             for (int e = 0; e < 4; ++e) am = fmaxf(am, fabsf(v[i][e])); }
;         am = wave_max(am);
;         const float sc = am > 0.f ? 7.f / am : 1.f;
; #pragma unroll
;         for (int i = 0; i < 8; ++i)
; #pragma unroll
;             for (int e = 0; e < 4; ++e) stg[F.lane * 33 + permL[i * 4 + e]] = v[i][e] * sc;
;         asm volatile("s_waitcnt lgkmcnt(0)" ::: "memory"); __builtin_amdgcn_wave_barrier(); asm volatile("" ::: "memory");
;         v16f lo, hi;
; #pragma unroll
;         for (int i = 0; i < 16; ++i) { lo[i] = stg[F.lane * 33 + i]; hi[i] = stg[F.lane * 33 + 16 + i]; }
;         asm volatile("s_waitcnt lgkmcnt(0)" ::: "memory"); __builtin_amdgcn_wave_barrier(); asm volatile("" ::: "memory");
;         const v6u w = __builtin_amdgcn_cvt_scalef32_2xpk16_fp6_f32(lo, hi, 1.0f);
;         unsigned char* d = dst + (size_t)row * EROW;
;         *(u32x4*)(d + F.lane * 16) = (u32x4){w[0], w[1], w[2], w[3]}; *(u32x2*)(d + 1024 + F.lane * 8) = (u32x2){w[4], w[5]};
.LBB0_960:
	global_load_dwordx4 v[4:7], v[36:37], off offset:-4096 nt
	global_load_dwordx4 v[8:11], v[36:37], off offset:-3072 nt
	global_load_dwordx4 v[12:15], v[36:37], off offset:-2048 nt
	global_load_dwordx4 v[16:19], v[36:37], off offset:-1024 nt
	global_load_dwordx4 v[20:23], v[36:37], off nt
	global_load_dwordx4 v[24:27], v[36:37], off offset:1024 nt
	global_load_dwordx4 v[28:31], v[36:37], off offset:2048 nt
	global_load_dwordx4 v[0:3], v[36:37], off offset:3072 nt
	ds_read_b128 v[42:45], v39
	ds_read_b128 v[46:49], v39 offset:16
	ds_read_b128 v[50:53], v39 offset:32
	ds_read_b128 v[54:57], v39 offset:48
	ds_read_b128 v[58:61], v39 offset:64
	ds_read_b128 v[62:65], v39 offset:80
	ds_read_b128 v[66:69], v39 offset:96
	ds_read_b128 v[70:73], v39 offset:112
	s_waitcnt lgkmcnt(7)
	v_lshl_add_u32 v42, v42, 2, v38
	v_lshl_add_u32 v43, v43, 2, v38
	v_lshl_add_u32 v44, v44, 2, v38
	v_lshl_add_u32 v45, v45, 2, v38
	s_waitcnt lgkmcnt(6)
	v_lshl_add_u32 v46, v46, 2, v38
	v_lshl_add_u32 v47, v47, 2, v38
	v_lshl_add_u32 v48, v48, 2, v38
	v_lshl_add_u32 v49, v49, 2, v38
	s_waitcnt lgkmcnt(5)
	v_lshl_add_u32 v50, v50, 2, v38
	v_lshl_add_u32 v51, v51, 2, v38
	v_lshl_add_u32 v52, v52, 2, v38
	v_lshl_add_u32 v53, v53, 2, v38
	s_waitcnt lgkmcnt(4)
	v_lshl_add_u32 v54, v54, 2, v38
	v_lshl_add_u32 v55, v55, 2, v38
	v_lshl_add_u32 v56, v56, 2, v38
	v_lshl_add_u32 v57, v57, 2, v38
	s_waitcnt lgkmcnt(3)
	v_lshl_add_u32 v58, v58, 2, v38
	v_lshl_add_u32 v59, v59, 2, v38
	v_lshl_add_u32 v60, v60, 2, v38
	v_lshl_add_u32 v61, v61, 2, v38
	s_waitcnt lgkmcnt(2)
	v_lshl_add_u32 v62, v62, 2, v38
	v_lshl_add_u32 v63, v63, 2, v38
	v_lshl_add_u32 v64, v64, 2, v38
	v_lshl_add_u32 v65, v65, 2, v38
	s_waitcnt lgkmcnt(1)
	v_lshl_add_u32 v66, v66, 2, v38
	v_lshl_add_u32 v67, v67, 2, v38
	v_lshl_add_u32 v68, v68, 2, v38
	s_waitcnt vmcnt(7)
	v_max3_f32 v41, |v4|, 0, |v5|
	v_max3_f32 v41, v41, |v6|, |v7|
	s_waitcnt vmcnt(6)
	v_max3_f32 v41, v41, |v8|, |v9|
	v_max3_f32 v41, v41, |v10|, |v11|
	s_waitcnt vmcnt(5)
	v_max3_f32 v41, v41, |v12|, |v13|
	v_max3_f32 v41, v41, |v14|, |v15|
	s_waitcnt vmcnt(4)
	v_max3_f32 v41, v41, |v16|, |v17|
	v_max3_f32 v41, v41, |v18|, |v19|
	s_waitcnt vmcnt(3)
	v_max3_f32 v41, v41, |v20|, |v21|
	v_max3_f32 v41, v41, |v22|, |v23|
	s_waitcnt vmcnt(2)
	v_max3_f32 v41, v41, |v24|, |v25|
	v_max3_f32 v41, v41, |v26|, |v27|
	s_waitcnt vmcnt(1)
	v_max3_f32 v41, v41, |v28|, |v29|
	v_max3_f32 v41, v41, |v30|, |v31|
	s_waitcnt vmcnt(0)
	v_max3_f32 v41, v41, |v0|, |v1|
	v_max3_f32 v41, v41, |v2|, |v3|
	ds_swizzle_b32 v74, v41 offset:swizzle(SWAP,16)
	s_waitcnt lgkmcnt(0)
	v_max_f32_e32 v74, v74, v74
	v_max_f32_e32 v41, v41, v74
	ds_swizzle_b32 v74, v41 offset:swizzle(SWAP,8)
	s_waitcnt lgkmcnt(0)
	v_max_f32_e32 v74, v74, v74
	v_max_f32_e32 v41, v41, v74
	ds_swizzle_b32 v74, v41 offset:swizzle(SWAP,4)
	s_waitcnt lgkmcnt(0)
	v_max_f32_e32 v74, v74, v74
	v_max_f32_e32 v41, v41, v74
	ds_swizzle_b32 v74, v41 offset:swizzle(SWAP,2)
	s_waitcnt lgkmcnt(0)
	v_max_f32_e32 v74, v74, v74
	v_max_f32_e32 v41, v41, v74
	ds_swizzle_b32 v74, v41 offset:swizzle(SWAP,1)
	s_waitcnt lgkmcnt(0)
	v_max_f32_e32 v74, v74, v74
	v_max_f32_e32 v41, v41, v74
	v_mov_b32_e32 v74, v41
	s_nop 1
	v_permlane32_swap_b32_e32 v41, v74
	v_max_f32_e32 v74, v74, v74
	v_max_f32_e32 v41, v41, v41
	v_max_f32_e32 v41, v41, v74
	v_div_scale_f32 v74, s[16:17], v41, v41, s7
	v_rcp_f32_e32 v75, v74
	v_div_scale_f32 v76, vcc, s7, v41, s7
	v_fma_f32 v78, -v74, v75, 1.0
	v_fmac_f32_e32 v75, v78, v75
	v_mul_f32_e32 v78, v76, v75
	v_fma_f32 v79, -v74, v78, v76
	v_fmac_f32_e32 v78, v79, v75
	v_fma_f32 v74, -v74, v78, v76
	v_div_fmas_f32 v74, v74, v75, v78
	v_div_fixup_f32 v74, v74, v41, s7
	v_cmp_lt_f32_e32 vcc, 0, v41
	s_nop 1
	v_cndmask_b32_e32 v74, 1.0, v74, vcc
	v_mul_f32_e32 v4, v4, v74
	v_mul_f32_e32 v5, v5, v74
	v_mul_f32_e32 v6, v6, v74
	v_mul_f32_e32 v7, v7, v74
	v_mul_f32_e32 v8, v8, v74
	v_mul_f32_e32 v9, v9, v74
	v_mul_f32_e32 v10, v10, v74
	v_mul_f32_e32 v11, v11, v74
	v_mul_f32_e32 v12, v12, v74
	v_mul_f32_e32 v13, v13, v74
	v_mul_f32_e32 v14, v14, v74
	v_mul_f32_e32 v15, v15, v74
	v_mul_f32_e32 v16, v16, v74
	v_mul_f32_e32 v17, v17, v74
	v_mul_f32_e32 v18, v18, v74
	v_mul_f32_e32 v19, v19, v74
	v_mul_f32_e32 v20, v20, v74
	v_mul_f32_e32 v21, v21, v74
	v_mul_f32_e32 v22, v22, v74
	v_mul_f32_e32 v23, v23, v74
	v_mul_f32_e32 v24, v24, v74
	v_mul_f32_e32 v25, v25, v74
	v_mul_f32_e32 v26, v26, v74
	v_mul_f32_e32 v27, v27, v74
	v_mul_f32_e32 v28, v28, v74
	v_mul_f32_e32 v29, v29, v74
	v_mul_f32_e32 v30, v30, v74
	v_mul_f32_e32 v31, v31, v74
	ds_write_b32 v42, v4
	ds_write_b32 v43, v5
	ds_write_b32 v44, v6
	ds_write_b32 v45, v7
	ds_write_b32 v46, v8
	ds_write_b32 v47, v9
	ds_write_b32 v48, v10
	ds_write_b32 v49, v11
	ds_write_b32 v50, v12
	ds_write_b32 v51, v13
	ds_write_b32 v52, v14
	ds_write_b32 v53, v15
	ds_write_b32 v54, v16
	ds_write_b32 v55, v17
	ds_write_b32 v56, v18
	ds_write_b32 v57, v19
	ds_write_b32 v58, v20
	ds_write_b32 v59, v21
	ds_write_b32 v60, v22
	ds_write_b32 v61, v23
	ds_write_b32 v62, v24
	ds_write_b32 v63, v25
	ds_write_b32 v64, v26
	ds_write_b32 v65, v27
	ds_write_b32 v66, v28
	ds_write_b32 v67, v29
	ds_write_b32 v68, v30
	v_lshl_add_u32 v4, v69, 2, v38
	ds_write_b32 v4, v31
	v_mul_f32_e32 v0, v0, v74
	v_lshl_add_u32 v4, v70, 2, v38
	v_mul_f32_e32 v1, v1, v74
	ds_write_b32 v4, v0
	v_lshl_add_u32 v0, v71, 2, v38
	ds_write_b32 v0, v1
	v_mul_f32_e32 v0, v2, v74
	v_lshl_add_u32 v2, v72, 2, v38
	v_mul_f32_e32 v1, v3, v74
	ds_write_b32 v2, v0
	v_lshl_add_u32 v0, v73, 2, v38
	ds_write_b32 v0, v1
	s_waitcnt lgkmcnt(0)
	ds_read2_b32 v[0:1], v38 offset1:1
	ds_read2_b32 v[2:3], v38 offset0:2 offset1:3
	ds_read2_b32 v[4:5], v38 offset0:4 offset1:5
	ds_read2_b32 v[6:7], v38 offset0:6 offset1:7
	ds_read2_b32 v[16:17], v38 offset0:16 offset1:17
	ds_read2_b32 v[18:19], v38 offset0:18 offset1:19
	ds_read2_b32 v[20:21], v38 offset0:20 offset1:21
	ds_read2_b32 v[22:23], v38 offset0:22 offset1:23
	ds_read2_b32 v[8:9], v38 offset0:8 offset1:9
	ds_read2_b32 v[10:11], v38 offset0:10 offset1:11
	ds_read2_b32 v[12:13], v38 offset0:12 offset1:13
	ds_read2_b32 v[14:15], v38 offset0:14 offset1:15
	ds_read2_b32 v[24:25], v38 offset0:24 offset1:25
	ds_read2_b32 v[26:27], v38 offset0:26 offset1:27
	ds_read2_b32 v[28:29], v38 offset0:28 offset1:29
	ds_read2_b32 v[30:31], v38 offset0:30 offset1:31
	s_waitcnt lgkmcnt(0)
	s_waitcnt lgkmcnt(0)
	v_cvt_scalef32_2xpk16_fp6_f32 v[0:5], v[0:15], v[16:31], 1.0
	global_store_dwordx4 v[34:35], v[0:3], off
	s_nop 1
	v_lshl_add_u64 v[0:1], v[34:35], 0, v[32:33]
	global_store_dwordx2 v[0:1], v[4:5], off offset:1024
	s_and_saveexec_b64 s[16:17], s[2:3]
	s_cbranch_execz .LBB0_959
; __device__ __forceinline__ void cvt_rows_fp6(const Ctx& F, const float* src, unsigned char* dst, float* descale, int R) {
;     ...
;         if (F.lane == 0) descale[row] = (am > 0.f ? am * (1.f / 7.f) : 1.f) / (fac > 0.f ? fac : 1.f);
	v_mul_f32_e32 v0, 0x3e124925, v41
	v_cndmask_b32_e32 v0, 1.0, v0, vcc
	v_div_scale_f32 v1, s[18:19], v77, v77, v0
	v_rcp_f32_e32 v2, v1
	v_div_scale_f32 v3, vcc, v0, v77, v0
	v_fma_f32 v4, -v1, v2, 1.0
	v_fmac_f32_e32 v2, v4, v2
	v_mul_f32_e32 v4, v3, v2
	v_fma_f32 v5, -v1, v4, v3
	v_fmac_f32_e32 v4, v5, v2
	v_fma_f32 v1, -v1, v4, v3
	v_div_fmas_f32 v1, v1, v2, v4
	v_div_fixup_f32 v0, v1, v77, v0
	global_store_dword v40, v0, s[12:13]
	s_branch .LBB0_959
